# NSA tile loop: PV V-fragment reads hoisted before the exp block (K reads left in place)
# baseline (speedup 1.0000x reference)
; #define LAS __attribute__((address_space(3)))
; DI float fexp2(float x) { return __builtin_amdgcn_exp2f(x); }
; DI f32x16 mfma32(bf16x8 a, bf16x8 b, f32x16 c) { return __builtin_amdgcn_mfma_f32_32x32x16_bf16(a, b, c, 0, 0, 0); }
; DI void pv_sub(const LAS unsigned char* vt, int vstride, int koff_bytes, const f32x16& p, f32x16 (&o)[2], int r, int hh) {
;     const bf16x8 pf0 = pack8<0>(p), pf1 = pack8<1>(p);
; #pragma unroll
;     for (int st = 0; st < 2; ++st) {
;         u32x2 lo[2], hi[2];
; #pragma unroll
;         for (int u = 0; u < 2; ++u) {
;             const LAS unsigned char* a = vt + (32 * u + r) * vstride + koff_bytes + 32 * st + 8 * hh;
;             lo[u] = *(const LAS u32x2*)a; hi[u] = *(const LAS u32x2*)(a + 16);
;         }
;         __builtin_amdgcn_sched_barrier(0);
; #pragma unroll
;         for (int u = 0; u < 2; ++u) { u32x4 v; v.x = lo[u].x; v.y = lo[u].y; v.z = hi[u].x; v.w = hi[u].y; o[u] = mfma32(__builtin_bit_cast(bf16x8, v), st ? pf1 : pf0, o[u]); }
;     }
; }
; DI void softmax_lazy(f32x16 (&s)[2], float& m, float& l, f32x16 (&o)[2], int hh) {
;     ...
;     float sum = 0.f;
; #pragma unroll
;     for (int t = 0; t < 2; ++t)
; #pragma unroll
;         for (int i = 0; i < 16; ++i) { s[t][i] = fexp2(s[t][i]); sum += s[t][i]; }
;     sum += __shfl_xor(sum, 32);
;     l += sum;
.LBB0_2419:
	v_add3_u32 v16, s0, v211, v242
	v_add_u32_e32 v17, 0xa800, v16
	v_add_u32_e32 v16, 0xb800, v16
	ds_read2_b64 v[20:23], v17 offset0:192 offset1:194
	ds_read2_b64 v[24:27], v16 offset0:224 offset1:226
	ds_read2_b64 v[28:31], v17 offset0:196 offset1:198
	ds_read2_b64 v[32:35], v16 offset0:228 offset1:230
	ds_read2_b64 v[36:39], v17 offset0:200 offset1:202
	ds_read2_b64 v[40:43], v16 offset0:232 offset1:234
	ds_read2_b64 v[44:47], v17 offset0:204 offset1:206
	ds_read2_b64 v[48:51], v16 offset0:236 offset1:238
	v_exp_f32_e32 v0, v160
	v_exp_f32_e32 v3, v161
	v_exp_f32_e32 v7, v162
	v_exp_f32_e32 v9, v163
	v_add_f32_e32 v2, 0, v0
	v_exp_f32_e32 v10, v164
	v_add_f32_e32 v2, v3, v2
	v_exp_f32_e32 v11, v165
	v_add_f32_e32 v2, v7, v2
	v_exp_f32_e32 v12, v166
	v_add_f32_e32 v2, v9, v2
	v_exp_f32_e32 v13, v167
	v_add_f32_e32 v2, v10, v2
	v_exp_f32_e32 v14, v168
	v_add_f32_e32 v2, v11, v2
	v_exp_f32_e32 v15, v169
	v_add_f32_e32 v2, v12, v2
	v_exp_f32_e32 v160, v170
	v_add_f32_e32 v2, v13, v2
	v_exp_f32_e32 v161, v171
	v_add_f32_e32 v2, v14, v2
	v_exp_f32_e32 v162, v172
	v_add_f32_e32 v2, v15, v2
	v_exp_f32_e32 v163, v173
	v_add_f32_e32 v2, v160, v2
	v_exp_f32_e32 v164, v174
	v_add_f32_e32 v2, v161, v2
	v_exp_f32_e32 v165, v175
	v_add_f32_e32 v2, v162, v2
	v_exp_f32_e32 v166, v144
	v_add_f32_e32 v2, v163, v2
	v_exp_f32_e32 v167, v145
	v_add_f32_e32 v2, v164, v2
	v_exp_f32_e32 v168, v146
	v_add_f32_e32 v2, v165, v2
	v_exp_f32_e32 v169, v147
	v_add_f32_e32 v2, v166, v2
	v_exp_f32_e32 v170, v148
	v_add_f32_e32 v2, v167, v2
	v_exp_f32_e32 v171, v149
	v_add_f32_e32 v2, v168, v2
	v_exp_f32_e32 v172, v150
	v_add_f32_e32 v2, v169, v2
	v_exp_f32_e32 v173, v151
	v_add_f32_e32 v2, v170, v2
	v_exp_f32_e32 v152, v152
	v_add_f32_e32 v2, v171, v2
	v_exp_f32_e32 v153, v153
	v_add_f32_e32 v2, v172, v2
	v_exp_f32_e32 v154, v154
	v_add_f32_e32 v2, v173, v2
	v_exp_f32_e32 v155, v155
	v_add_f32_e32 v2, v152, v2
	v_exp_f32_e32 v156, v156
	v_add_f32_e32 v2, v153, v2
	v_exp_f32_e32 v157, v157
	v_add_f32_e32 v2, v154, v2
	v_exp_f32_e32 v158, v158
	v_add_f32_e32 v2, v155, v2
	v_exp_f32_e32 v159, v159
	v_add_f32_e32 v2, v156, v2
	v_add_f32_e32 v2, v157, v2
	v_add_f32_e32 v2, v158, v2
	v_add_f32_e32 v2, v159, v2
	v_mov_b32_e32 v8, v2
	v_cvt_pk_bf16_f32 v9, v7, v9
	v_cvt_pk_bf16_f32 v10, v10, v11
	v_cvt_pk_bf16_f32 v11, v12, v13
	v_cvt_pk_bf16_f32 v12, v14, v15
	v_permlane32_swap_b32_e32 v8, v2
	v_add_f32_e32 v2, v2, v8
	v_cvt_pk_bf16_f32 v8, v0, v3
	v_add_f32_e32 v245, v245, v2
	v_cvt_pk_bf16_f32 v13, v160, v161
	v_cvt_pk_bf16_f32 v14, v162, v163
	v_cvt_pk_bf16_f32 v15, v164, v165
	s_waitcnt lgkmcnt(0)
	v_mfma_f32_32x32x16_bf16 v[128:143], v[20:23], v[8:11], v[128:143]
	v_mfma_f32_32x32x16_bf16 v[112:127], v[24:27], v[8:11], v[112:127]
	v_mfma_f32_32x32x16_bf16 v[128:143], v[28:31], v[12:15], v[128:143]
	v_cvt_pk_bf16_f32 v8, v166, v167
	v_cvt_pk_bf16_f32 v9, v168, v169
	v_cvt_pk_bf16_f32 v10, v170, v171
	v_cvt_pk_bf16_f32 v11, v172, v173
	v_mfma_f32_32x32x16_bf16 v[112:127], v[32:35], v[12:15], v[112:127]
	v_cvt_pk_bf16_f32 v12, v152, v153
	v_cvt_pk_bf16_f32 v13, v154, v155
	v_cvt_pk_bf16_f32 v14, v156, v157
	v_cvt_pk_bf16_f32 v15, v158, v159
	v_mfma_f32_32x32x16_bf16 v[128:143], v[36:39], v[8:11], v[128:143]
	v_mfma_f32_32x32x16_bf16 v[112:127], v[40:43], v[8:11], v[112:127]
	v_mfma_f32_32x32x16_bf16 v[128:143], v[44:47], v[12:15], v[128:143]
	v_mfma_f32_32x32x16_bf16 v[112:127], v[48:51], v[12:15], v[112:127]
